# out-proj EpiRes<false> epilogue: 16-step load/wait/store ladder software-pipelined 3 row-groups deep with counted vmcnt
# speedup vs baseline: 1.0068x; 1.0068x over previous
.LBB0_780:
	v_add_u32_e32 v30, s15, v202
	ds_read_b128 v[18:21], v30
	ds_read_b128 v[22:25], v30 offset:1024
	ds_read_b128 v[26:29], v30 offset:2048
	ds_read_b128 v[30:33], v30 offset:3072
	s_add_u32 s0, s20, 0xfffc0080
	s_addc_u32 s1, s21, -1
	s_cmp_eq_u32 s28, 12
	s_cselect_b32 s51, s8, s1
	s_cselect_b32 s50, s10, s0
	s_cselect_b32 s35, s11, s26
	s_cselect_b32 s34, s24, s25
	v_lshl_add_u64 v[184:185], s[20:21], 0, v[180:181]
	s_add_i32 m0, s61, 0xc000
	ds_read_b128 v[34:37], v204
	ds_read_b128 v[38:41], v204 offset:1024
	ds_read_b128 v[58:61], v204 offset:2048
	ds_read_b128 v[62:65], v204 offset:3072
	ds_read_b128 v[66:69], v204 offset:4096
	ds_read_b128 v[70:73], v204 offset:5120
	ds_read_b128 v[74:77], v204 offset:6144
	ds_read_b128 v[78:81], v204 offset:7168
	global_load_lds_dwordx4 v[184:185], off
	v_lshl_add_u64 v[184:185], s[20:21], 0, v[182:183]
	s_add_i32 m0, s61, 0xe000
	s_nop 0
	global_load_lds_dwordx4 v[184:185], off
	s_waitcnt lgkmcnt(8)
	s_barrier
	s_waitcnt lgkmcnt(0)
	s_setprio 1
	s_waitcnt lgkmcnt(0)
	v_mfma_f32_16x16x32_bf16 v[174:177], v[18:21], v[34:37], v[174:177]
	v_mfma_f32_16x16x32_bf16 v[170:173], v[26:29], v[34:37], v[170:173]
	v_mfma_f32_16x16x32_bf16 v[158:161], v[18:21], v[58:61], v[158:161]
	v_mfma_f32_16x16x32_bf16 v[154:157], v[26:29], v[58:61], v[154:157]
	v_mfma_f32_16x16x32_bf16 v[142:145], v[18:21], v[66:69], v[142:145]
	v_mfma_f32_16x16x32_bf16 v[138:141], v[26:29], v[66:69], v[138:141]
	v_mfma_f32_16x16x32_bf16 v[126:129], v[18:21], v[74:77], v[126:129]
	v_mfma_f32_16x16x32_bf16 v[122:125], v[26:29], v[74:77], v[122:125]
	v_mfma_f32_16x16x32_bf16 v[174:177], v[22:25], v[38:41], v[174:177]
	v_mfma_f32_16x16x32_bf16 v[170:173], v[30:33], v[38:41], v[170:173]
	v_mfma_f32_16x16x32_bf16 v[158:161], v[22:25], v[62:65], v[158:161]
	v_mfma_f32_16x16x32_bf16 v[154:157], v[30:33], v[62:65], v[154:157]
	v_mfma_f32_16x16x32_bf16 v[142:145], v[22:25], v[70:73], v[142:145]
	v_mfma_f32_16x16x32_bf16 v[138:141], v[30:33], v[70:73], v[138:141]
	v_mfma_f32_16x16x32_bf16 v[126:129], v[22:25], v[78:81], v[126:129]
	v_mfma_f32_16x16x32_bf16 v[122:125], v[30:33], v[78:81], v[122:125]
	s_setprio 0
	s_barrier
	v_add_u32_e32 v188, s63, v202
	s_mov_b32 m0, s55
	ds_read_b128 v[184:187], v188
	ds_read_b128 v[206:209], v188 offset:1024
	ds_read_b128 v[210:213], v188 offset:2048
	ds_read_b128 v[214:217], v188 offset:3072
	v_lshl_add_u64 v[188:189], s[34:35], 0, v[0:1]
	global_load_lds_dwordx4 v[188:189], off
	v_lshl_add_u64 v[222:223], s[34:35], 0, v[178:179]
	s_mov_b32 m0, s60
	s_nop 0
	global_load_lds_dwordx4 v[222:223], off
	s_barrier
	s_waitcnt lgkmcnt(0)
	s_setprio 1
	s_waitcnt lgkmcnt(0)
	v_mfma_f32_16x16x32_bf16 v[166:169], v[184:187], v[34:37], v[166:169]
	v_mfma_f32_16x16x32_bf16 v[34:37], v[210:213], v[34:37], v[162:165]
	v_mfma_f32_16x16x32_bf16 v[166:169], v[206:209], v[38:41], v[166:169]
	v_mfma_f32_16x16x32_bf16 v[34:37], v[214:217], v[38:41], v[34:37]
	v_mfma_f32_16x16x32_bf16 v[38:41], v[184:187], v[58:61], v[150:153]
	v_mfma_f32_16x16x32_bf16 v[58:61], v[210:213], v[58:61], v[146:149]
	v_mfma_f32_16x16x32_bf16 v[38:41], v[206:209], v[62:65], v[38:41]
	v_mfma_f32_16x16x32_bf16 v[58:61], v[214:217], v[62:65], v[58:61]
	v_mfma_f32_16x16x32_bf16 v[62:65], v[184:187], v[66:69], v[134:137]
	v_mfma_f32_16x16x32_bf16 v[66:69], v[210:213], v[66:69], v[130:133]
	v_mfma_f32_16x16x32_bf16 v[62:65], v[206:209], v[70:73], v[62:65]
	v_mfma_f32_16x16x32_bf16 v[66:69], v[214:217], v[70:73], v[66:69]
	v_mfma_f32_16x16x32_bf16 v[70:73], v[184:187], v[74:77], v[118:121]
	v_mfma_f32_16x16x32_bf16 v[74:77], v[210:213], v[74:77], v[114:117]
	v_mfma_f32_16x16x32_bf16 v[70:73], v[206:209], v[78:81], v[70:73]
	v_mfma_f32_16x16x32_bf16 v[74:77], v[214:217], v[78:81], v[74:77]
	s_setprio 0
	s_mov_b32 m0, s61
	v_lshl_add_u64 v[250:251], s[50:51], 0, v[0:1]
	s_barrier
	ds_read_b128 v[78:81], v204 offset:16384
	ds_read_b128 v[114:117], v204 offset:17408
	ds_read_b128 v[118:121], v204 offset:18432
	ds_read_b128 v[130:133], v204 offset:19456
	ds_read_b128 v[134:137], v204 offset:20480
	ds_read_b128 v[146:149], v204 offset:21504
	ds_read_b128 v[150:153], v204 offset:22528
	ds_read_b128 v[162:165], v204 offset:23552
	global_load_lds_dwordx4 v[250:251], off
	v_lshl_add_u64 v[232:233], s[50:51], 0, v[178:179]
	s_mov_b32 m0, s62
	s_nop 0
	global_load_lds_dwordx4 v[232:233], off
	s_barrier
	s_waitcnt lgkmcnt(0)
	s_setprio 1
	s_waitcnt lgkmcnt(0)
	v_mfma_f32_16x16x32_bf16 v[110:113], v[18:21], v[78:81], v[110:113]
	v_mfma_f32_16x16x32_bf16 v[106:109], v[26:29], v[78:81], v[106:109]
	v_mfma_f32_16x16x32_bf16 v[94:97], v[18:21], v[118:121], v[94:97]
	v_mfma_f32_16x16x32_bf16 v[90:93], v[26:29], v[118:121], v[90:93]
	v_mfma_f32_16x16x32_bf16 v[54:57], v[18:21], v[134:137], v[54:57]
	v_mfma_f32_16x16x32_bf16 v[50:53], v[26:29], v[134:137], v[50:53]
	v_mfma_f32_16x16x32_bf16 v[14:17], v[18:21], v[150:153], v[14:17]
	v_mfma_f32_16x16x32_bf16 v[10:13], v[26:29], v[150:153], v[10:13]
	v_mfma_f32_16x16x32_bf16 v[110:113], v[22:25], v[114:117], v[110:113]
	v_mfma_f32_16x16x32_bf16 v[106:109], v[30:33], v[114:117], v[106:109]
	v_mfma_f32_16x16x32_bf16 v[94:97], v[22:25], v[130:133], v[94:97]
	v_mfma_f32_16x16x32_bf16 v[90:93], v[30:33], v[130:133], v[90:93]
	v_mfma_f32_16x16x32_bf16 v[54:57], v[22:25], v[146:149], v[54:57]
	v_mfma_f32_16x16x32_bf16 v[50:53], v[30:33], v[146:149], v[50:53]
	v_mfma_f32_16x16x32_bf16 v[14:17], v[22:25], v[162:165], v[14:17]
	v_mfma_f32_16x16x32_bf16 v[10:13], v[30:33], v[162:165], v[10:13]
	s_setprio 0
	s_barrier
	s_add_u32 s0, s34, 0x40000
	s_addc_u32 s1, s35, 0
	s_mov_b32 m0, s66
	v_lshl_add_u64 v[18:19], s[0:1], 0, v[0:1]
	global_load_lds_dwordx4 v[18:19], off
	v_lshl_add_u64 v[18:19], s[0:1], 0, v[178:179]
	s_mov_b32 m0, s67
	s_nop 0
	global_load_lds_dwordx4 v[18:19], off
	s_waitcnt vmcnt(6)
	s_barrier
	s_setprio 1
	v_mfma_f32_16x16x32_bf16 v[46:49], v[184:187], v[134:137], v[46:49]
	v_mfma_f32_16x16x32_bf16 v[42:45], v[210:213], v[134:137], v[42:45]
	v_mfma_f32_16x16x32_bf16 v[6:9], v[184:187], v[150:153], v[6:9]
	v_mfma_f32_16x16x32_bf16 v[2:5], v[210:213], v[150:153], v[2:5]
	v_mfma_f32_16x16x32_bf16 v[18:21], v[184:187], v[78:81], v[102:105]
	v_mfma_f32_16x16x32_bf16 v[22:25], v[210:213], v[78:81], v[98:101]
	v_mfma_f32_16x16x32_bf16 v[26:29], v[184:187], v[118:121], v[86:89]
	v_mfma_f32_16x16x32_bf16 v[30:33], v[210:213], v[118:121], v[82:85]
	v_mfma_f32_16x16x32_bf16 v[46:49], v[206:209], v[146:149], v[46:49]
	v_mfma_f32_16x16x32_bf16 v[42:45], v[214:217], v[146:149], v[42:45]
	v_mfma_f32_16x16x32_bf16 v[6:9], v[206:209], v[162:165], v[6:9]
	v_mfma_f32_16x16x32_bf16 v[2:5], v[214:217], v[162:165], v[2:5]
	v_mfma_f32_16x16x32_bf16 v[18:21], v[206:209], v[114:117], v[18:21]
	v_mfma_f32_16x16x32_bf16 v[22:25], v[214:217], v[114:117], v[22:25]
	v_mfma_f32_16x16x32_bf16 v[26:29], v[206:209], v[130:133], v[26:29]
	v_mfma_f32_16x16x32_bf16 v[30:33], v[214:217], v[130:133], v[30:33]
	s_setprio 0
	v_add_u32_e32 v98, s72, v202
	s_barrier
	ds_read_b128 v[78:81], v98
	ds_read_b128 v[82:85], v98 offset:1024
	ds_read_b128 v[86:89], v98 offset:2048
	ds_read_b128 v[98:101], v98 offset:3072
	s_add_u32 s0, s50, 0x40000
	s_addc_u32 s1, s51, 0
	s_mov_b32 m0, s68
	v_lshl_add_u64 v[134:135], s[0:1], 0, v[0:1]
	ds_read_b128 v[102:105], v204 offset:32768
	ds_read_b128 v[114:117], v204 offset:33792
	ds_read_b128 v[118:121], v204 offset:34816
	ds_read_b128 v[130:133], v204 offset:35840
	ds_read_b128 v[184:187], v204 offset:36864
	ds_read_b128 v[206:209], v204 offset:37888
	ds_read_b128 v[210:213], v204 offset:38912
	ds_read_b128 v[214:217], v204 offset:39936
	global_load_lds_dwordx4 v[134:135], off
	v_lshl_add_u64 v[134:135], s[0:1], 0, v[178:179]
	s_mov_b32 m0, s69
	s_nop 0
	global_load_lds_dwordx4 v[134:135], off
	s_waitcnt lgkmcnt(8)
	s_barrier
	s_waitcnt lgkmcnt(0)
	s_setprio 1
	s_waitcnt lgkmcnt(0)
	v_mfma_f32_16x16x32_bf16 v[134:137], v[78:81], v[102:105], v[174:177]
	v_mfma_f32_16x16x32_bf16 v[174:177], v[82:85], v[114:117], v[134:137]
	v_mfma_f32_16x16x32_bf16 v[134:137], v[86:89], v[102:105], v[170:173]
	v_mfma_f32_16x16x32_bf16 v[170:173], v[98:101], v[114:117], v[134:137]
	v_mfma_f32_16x16x32_bf16 v[134:137], v[78:81], v[118:121], v[158:161]
	v_mfma_f32_16x16x32_bf16 v[158:161], v[82:85], v[130:133], v[134:137]
	v_mfma_f32_16x16x32_bf16 v[134:137], v[86:89], v[118:121], v[154:157]
	v_mfma_f32_16x16x32_bf16 v[154:157], v[98:101], v[130:133], v[134:137]
	v_mfma_f32_16x16x32_bf16 v[134:137], v[78:81], v[184:187], v[142:145]
	v_mfma_f32_16x16x32_bf16 v[142:145], v[82:85], v[206:209], v[134:137]
	v_mfma_f32_16x16x32_bf16 v[134:137], v[86:89], v[184:187], v[138:141]
	v_mfma_f32_16x16x32_bf16 v[126:129], v[78:81], v[210:213], v[126:129]
	v_mfma_f32_16x16x32_bf16 v[122:125], v[86:89], v[210:213], v[122:125]
	v_mfma_f32_16x16x32_bf16 v[138:141], v[98:101], v[206:209], v[134:137]
	v_mfma_f32_16x16x32_bf16 v[126:129], v[82:85], v[214:217], v[126:129]
	v_mfma_f32_16x16x32_bf16 v[122:125], v[98:101], v[214:217], v[122:125]
	s_setprio 0
	s_barrier
	s_nop 0
	v_add_u32_e32 v134, s77, v202
	s_mov_b32 m0, s73
	ds_read_b128 v[218:221], v134
	ds_read_b128 v[242:245], v134 offset:1024
	ds_read_b128 v[246:249], v134 offset:2048
	ds_read_b128 v[194:197], v134 offset:3072
	v_lshl_add_u64 v[134:135], v[188:189], 0, s[88:89]
	global_load_lds_dwordx4 v[134:135], off
	v_lshl_add_u64 v[134:135], v[222:223], 0, s[88:89]
	s_mov_b32 m0, s74
	s_nop 0
	global_load_lds_dwordx4 v[134:135], off
	s_barrier
	s_waitcnt lgkmcnt(0)
	s_setprio 1
	s_waitcnt lgkmcnt(0)
	v_mfma_f32_16x16x32_bf16 v[34:37], v[246:249], v[102:105], v[34:37]
	v_mfma_f32_16x16x32_bf16 v[162:165], v[194:197], v[114:117], v[34:37]
	v_mfma_f32_16x16x32_bf16 v[34:37], v[218:221], v[118:121], v[38:41]
	v_mfma_f32_16x16x32_bf16 v[150:153], v[242:245], v[130:133], v[34:37]
	v_mfma_f32_16x16x32_bf16 v[34:37], v[246:249], v[118:121], v[58:61]
	v_mfma_f32_16x16x32_bf16 v[134:137], v[218:221], v[102:105], v[166:169]
	v_mfma_f32_16x16x32_bf16 v[146:149], v[194:197], v[130:133], v[34:37]
	v_mfma_f32_16x16x32_bf16 v[34:37], v[218:221], v[184:187], v[62:65]
	v_mfma_f32_16x16x32_bf16 v[166:169], v[242:245], v[114:117], v[134:137]
	v_mfma_f32_16x16x32_bf16 v[134:137], v[242:245], v[206:209], v[34:37]
	v_mfma_f32_16x16x32_bf16 v[34:37], v[246:249], v[184:187], v[66:69]
	v_mfma_f32_16x16x32_bf16 v[130:133], v[194:197], v[206:209], v[34:37]
	v_mfma_f32_16x16x32_bf16 v[34:37], v[218:221], v[210:213], v[70:73]
	v_mfma_f32_16x16x32_bf16 v[118:121], v[242:245], v[214:217], v[34:37]
	v_mfma_f32_16x16x32_bf16 v[34:37], v[246:249], v[210:213], v[74:77]
	v_mfma_f32_16x16x32_bf16 v[114:117], v[194:197], v[214:217], v[34:37]
	s_setprio 0
	s_mov_b32 m0, s75
	v_lshl_add_u64 v[102:103], v[250:251], 0, s[88:89]
	s_barrier
	s_nop 2
	ds_read_b128 v[34:37], v204 offset:49152
	ds_read_b128 v[38:41], v204 offset:50176
	ds_read_b128 v[58:61], v204 offset:51200
	ds_read_b128 v[62:65], v204 offset:52224
	ds_read_b128 v[66:69], v204 offset:53248
	ds_read_b128 v[70:73], v204 offset:54272
	ds_read_b128 v[74:77], v204 offset:55296
	ds_read_b128 v[184:187], v204 offset:56320
	global_load_lds_dwordx4 v[102:103], off
	v_lshl_add_u64 v[102:103], v[232:233], 0, s[88:89]
	s_mov_b32 m0, s76
	s_nop 0
	global_load_lds_dwordx4 v[102:103], off
	s_barrier
	s_waitcnt lgkmcnt(0)
	s_setprio 1
	s_waitcnt lgkmcnt(0)
	v_mfma_f32_16x16x32_bf16 v[102:105], v[78:81], v[34:37], v[110:113]
	v_mfma_f32_16x16x32_bf16 v[110:113], v[82:85], v[38:41], v[102:105]
	v_mfma_f32_16x16x32_bf16 v[102:105], v[86:89], v[34:37], v[106:109]
	v_mfma_f32_16x16x32_bf16 v[94:97], v[78:81], v[58:61], v[94:97]
	v_mfma_f32_16x16x32_bf16 v[90:93], v[86:89], v[58:61], v[90:93]
	v_mfma_f32_16x16x32_bf16 v[54:57], v[78:81], v[66:69], v[54:57]
	v_mfma_f32_16x16x32_bf16 v[50:53], v[86:89], v[66:69], v[50:53]
	v_mfma_f32_16x16x32_bf16 v[14:17], v[78:81], v[74:77], v[14:17]
	v_mfma_f32_16x16x32_bf16 v[10:13], v[86:89], v[74:77], v[10:13]
	v_mfma_f32_16x16x32_bf16 v[106:109], v[98:101], v[38:41], v[102:105]
	v_mfma_f32_16x16x32_bf16 v[94:97], v[82:85], v[62:65], v[94:97]
	v_mfma_f32_16x16x32_bf16 v[90:93], v[98:101], v[62:65], v[90:93]
	v_mfma_f32_16x16x32_bf16 v[54:57], v[82:85], v[70:73], v[54:57]
	v_mfma_f32_16x16x32_bf16 v[50:53], v[98:101], v[70:73], v[50:53]
	v_mfma_f32_16x16x32_bf16 v[14:17], v[82:85], v[184:187], v[14:17]
	v_mfma_f32_16x16x32_bf16 v[10:13], v[98:101], v[184:187], v[10:13]
	s_setprio 0
	s_barrier
	s_add_u32 s0, s34, 0x40080
	s_addc_u32 s1, s35, 0
	s_mov_b32 m0, s78
	v_lshl_add_u64 v[78:79], s[0:1], 0, v[0:1]
	global_load_lds_dwordx4 v[78:79], off
	v_lshl_add_u64 v[78:79], s[0:1], 0, v[178:179]
	s_mov_b32 m0, s79
	s_nop 0
	global_load_lds_dwordx4 v[78:79], off
	s_waitcnt vmcnt(6)
	s_barrier
	s_setprio 1
	v_mfma_f32_16x16x32_bf16 v[18:21], v[218:221], v[34:37], v[18:21]
	v_mfma_f32_16x16x32_bf16 v[102:105], v[242:245], v[38:41], v[18:21]
	v_mfma_f32_16x16x32_bf16 v[18:21], v[246:249], v[34:37], v[22:25]
	v_mfma_f32_16x16x32_bf16 v[98:101], v[194:197], v[38:41], v[18:21]
	v_mfma_f32_16x16x32_bf16 v[18:21], v[218:221], v[58:61], v[26:29]
	v_mfma_f32_16x16x32_bf16 v[86:89], v[242:245], v[62:65], v[18:21]
	v_mfma_f32_16x16x32_bf16 v[18:21], v[246:249], v[58:61], v[30:33]
	v_mfma_f32_16x16x32_bf16 v[82:85], v[194:197], v[62:65], v[18:21]
	v_mfma_f32_16x16x32_bf16 v[18:21], v[218:221], v[66:69], v[46:49]
	v_mfma_f32_16x16x32_bf16 v[46:49], v[242:245], v[70:73], v[18:21]
	v_mfma_f32_16x16x32_bf16 v[18:21], v[246:249], v[66:69], v[42:45]
	v_mfma_f32_16x16x32_bf16 v[6:9], v[218:221], v[74:77], v[6:9]
	v_mfma_f32_16x16x32_bf16 v[2:5], v[246:249], v[74:77], v[2:5]
	v_mfma_f32_16x16x32_bf16 v[42:45], v[194:197], v[70:73], v[18:21]
	v_mfma_f32_16x16x32_bf16 v[6:9], v[242:245], v[184:187], v[6:9]
	v_mfma_f32_16x16x32_bf16 v[2:5], v[194:197], v[184:187], v[2:5]
	s_setprio 0
	s_add_i32 s28, s28, 2
	s_add_u32 s20, s20, 0x100
	s_addc_u32 s21, s21, 0
	s_add_u32 s25, s25, 0x100
	s_addc_u32 s26, s26, 0
	s_cmp_gt_u32 s28, 13
	s_barrier
	s_cbranch_scc0 .LBB0_780
	v_lshl_or_b32 v184, s4, 8, v203
	s_lshl_b32 s4, s14, 8
	s_add_i32 s0, s4, 0xfffff000
	s_lshr_b32 s0, s0, 11
	s_mulk_i32 s0, 0x1800
	s_addk_i32 s0, 0x1800
	s_cmp_gt_i32 s14, 15
	s_cselect_b32 s86, s0, 0
	v_add_u32_e32 v186, s4, v201
	s_lshl_b64 s[0:1], s[86:87], 2
	v_ashrrev_i32_e32 v187, 31, v186
	s_add_u32 s0, s70, s0
	v_ashrrev_i32_e32 v185, 31, v184
	v_lshlrev_b64 v[188:189], 11, v[186:187]
	s_addc_u32 s1, s71, s1
	v_lshlrev_b64 v[18:19], 2, v[184:185]
	v_lshl_add_u64 v[188:189], s[12:13], 0, v[188:189]
	v_lshlrev_b64 v[184:185], 1, v[184:185]
	v_lshl_add_u64 v[22:23], s[0:1], 0, v[18:19]
	v_lshl_add_u64 v[30:31], s[2:3], 0, v[18:19]
	v_lshl_add_u64 v[38:39], s[16:17], 0, v[18:19]
	v_lshl_add_u64 v[194:195], v[186:187], 3, s[6:7]
	v_lshl_add_u64 v[188:189], v[188:189], 0, v[184:185]
	v_mov_b64_e32 v[184:185], v[188:189]
	global_load_dwordx4 v[58:61], v[22:23], off offset:16
	global_load_dwordx4 v[62:65], v[22:23], off
	global_load_dwordx4 v[66:69], v[30:31], off offset:16
	global_load_dwordx4 v[74:77], v[30:31], off
	global_load_dwordx4 v[70:73], v[38:39], off offset:16
	global_load_dwordx4 v[78:81], v[38:39], off
	global_load_dwordx4 v[18:21], v[22:23], off offset:528
	s_nop 0
	global_load_dwordx4 v[22:25], v[22:23], off offset:512
	s_nop 0
	global_load_dwordx4 v[26:29], v[30:31], off offset:528
	global_load_dwordx4 v[34:37], v[30:31], off offset:512
	s_nop 0
	global_load_dwordx4 v[30:33], v[38:39], off offset:528
	s_nop 0
	global_load_dwordx4 v[38:41], v[38:39], off offset:512
	s_and_b64 vcc, exec, s[40:41]
	global_load_dwordx2 v[232:233], v[194:195], off
	global_load_dwordx4 v[210:213], v[188:189], off
	global_load_dwordx4 v[214:217], v[188:189], off offset:256
	s_mov_b32 s0, 0x8000
	s_mov_b32 s1, 0
	v_lshl_add_u64 v[188:189], v[188:189], 0, s[0:1]
	global_load_dwordx2 v[250:251], v[194:195], off offset:128
	global_load_dwordx4 v[242:245], v[188:189], off
	global_load_dwordx4 v[246:249], v[188:189], off offset:256
	v_lshl_add_u64 v[188:189], v[188:189], 0, s[0:1]
	global_load_dwordx2 v[222:223], v[194:195], off offset:256
	global_load_dwordx4 v[218:221], v[188:189], off
	global_load_dwordx4 v[206:209], v[188:189], off offset:256
	v_lshl_add_u64 v[188:189], v[188:189], 0, s[0:1]
	s_mov_b32 s4, s42
	s_mov_b32 s14, s44
	s_mov_b64 s[34:35], s[48:49]
	s_mov_b64 s[20:21], s[46:47]
	s_waitcnt vmcnt(7)
	v_lshlrev_b32_e32 v196, 16, v210
	v_and_b32_e32 v197, 0xffff0000, v210
	v_lshlrev_b32_e32 v210, 16, v211
	v_and_b32_e32 v211, 0xffff0000, v211
	v_lshlrev_b32_e32 v186, 16, v212
	v_and_b32_e32 v187, 0xffff0000, v212
	v_lshlrev_b32_e32 v212, 16, v213
	v_and_b32_e32 v213, 0xffff0000, v213
	v_sub_f32_e32 v211, v211, v232
	v_sub_f32_e32 v210, v210, v232
	v_sub_f32_e32 v197, v197, v232
	v_sub_f32_e32 v196, v196, v232
	v_pk_mul_f32 v[196:197], v[232:233], v[196:197] op_sel:[1,0]
	v_pk_mul_f32 v[210:211], v[232:233], v[210:211] op_sel:[1,0]
	v_sub_f32_e32 v213, v213, v232
	v_sub_f32_e32 v212, v212, v232
	v_sub_f32_e32 v187, v187, v232
	v_sub_f32_e32 v186, v186, v232
	v_pk_fma_f32 v[210:211], v[76:77], v[210:211], v[80:81]
	v_pk_fma_f32 v[196:197], v[74:75], v[196:197], v[78:79]
	v_pk_mul_f32 v[186:187], v[232:233], v[186:187] op_sel:[1,0]
	v_pk_mul_f32 v[212:213], v[232:233], v[212:213] op_sel:[1,0]
	v_pk_fma_f32 v[186:187], v[66:67], v[186:187], v[70:71]
	v_pk_fma_f32 v[212:213], v[68:69], v[212:213], v[72:73]
	v_pk_mul_f32 v[210:211], v[210:211], s[56:57] op_sel_hi:[1,0]
	v_pk_mul_f32 v[196:197], v[196:197], s[56:57] op_sel_hi:[1,0]
	v_pk_mul_f32 v[212:213], v[212:213], s[56:57] op_sel_hi:[1,0]
	v_pk_mul_f32 v[186:187], v[186:187], s[56:57] op_sel_hi:[1,0]
	v_pk_fma_f32 v[176:177], v[176:177], v[64:65], v[210:211]
	v_pk_fma_f32 v[174:175], v[174:175], v[62:63], v[196:197]
	v_pk_fma_f32 v[172:173], v[172:173], v[60:61], v[212:213]
	v_pk_fma_f32 v[170:171], v[170:171], v[58:59], v[186:187]
	v_cvt_pk_bf16_f32 v174, v174, v175
	v_cvt_pk_bf16_f32 v175, v176, v177
	v_cvt_pk_bf16_f32 v176, v170, v171
	v_cvt_pk_bf16_f32 v177, v172, v173
	global_store_dwordx4 v[184:185], v[174:177], off
	s_waitcnt vmcnt(7)
	v_lshlrev_b32_e32 v196, 16, v214
	v_and_b32_e32 v197, 0xffff0000, v214
	v_lshlrev_b32_e32 v214, 16, v215
	v_and_b32_e32 v215, 0xffff0000, v215
	v_lshlrev_b32_e32 v186, 16, v216
	v_and_b32_e32 v187, 0xffff0000, v216
	v_lshlrev_b32_e32 v216, 16, v217
	v_and_b32_e32 v217, 0xffff0000, v217
	v_sub_f32_e32 v215, v215, v232
	v_sub_f32_e32 v214, v214, v232
	v_sub_f32_e32 v197, v197, v232
	v_sub_f32_e32 v196, v196, v232
	v_pk_mul_f32 v[196:197], v[232:233], v[196:197] op_sel:[1,0]
	v_pk_mul_f32 v[214:215], v[232:233], v[214:215] op_sel:[1,0]
	v_sub_f32_e32 v217, v217, v232
	v_sub_f32_e32 v216, v216, v232
	v_sub_f32_e32 v187, v187, v232
	v_sub_f32_e32 v186, v186, v232
	v_pk_fma_f32 v[214:215], v[36:37], v[214:215], v[40:41]
	v_pk_fma_f32 v[196:197], v[34:35], v[196:197], v[38:39]
	v_pk_mul_f32 v[186:187], v[232:233], v[186:187] op_sel:[1,0]
	v_pk_mul_f32 v[216:217], v[232:233], v[216:217] op_sel:[1,0]
	v_pk_fma_f32 v[186:187], v[26:27], v[186:187], v[30:31]
	v_pk_fma_f32 v[216:217], v[28:29], v[216:217], v[32:33]
	v_pk_mul_f32 v[214:215], v[214:215], s[56:57] op_sel_hi:[1,0]
	v_pk_mul_f32 v[196:197], v[196:197], s[56:57] op_sel_hi:[1,0]
	v_pk_mul_f32 v[216:217], v[216:217], s[56:57] op_sel_hi:[1,0]
	v_pk_mul_f32 v[186:187], v[186:187], s[56:57] op_sel_hi:[1,0]
	v_pk_fma_f32 v[168:169], v[168:169], v[24:25], v[214:215]
	v_pk_fma_f32 v[166:167], v[166:167], v[22:23], v[196:197]
	v_pk_fma_f32 v[164:165], v[164:165], v[20:21], v[216:217]
	v_pk_fma_f32 v[162:163], v[162:163], v[18:19], v[186:187]
	v_cvt_pk_bf16_f32 v166, v166, v167
	v_cvt_pk_bf16_f32 v167, v168, v169
	v_cvt_pk_bf16_f32 v168, v162, v163
	v_cvt_pk_bf16_f32 v169, v164, v165
	global_store_dwordx4 v[184:185], v[166:169], off offset:256
	v_lshl_add_u64 v[184:185], v[184:185], 0, s[0:1]
	global_load_dwordx2 v[232:233], v[194:195], off offset:384
	global_load_dwordx4 v[210:213], v[188:189], off
	global_load_dwordx4 v[214:217], v[188:189], off offset:256
	s_mov_b32 s0, 0x28000
	v_lshl_add_u64 v[188:189], v[188:189], 0, s[0:1]
	s_waitcnt vmcnt(9)
	v_lshlrev_b32_e32 v196, 16, v242
	v_and_b32_e32 v197, 0xffff0000, v242
	v_lshlrev_b32_e32 v242, 16, v243
	v_and_b32_e32 v243, 0xffff0000, v243
	v_lshlrev_b32_e32 v186, 16, v244
	v_and_b32_e32 v187, 0xffff0000, v244
	v_lshlrev_b32_e32 v244, 16, v245
	v_and_b32_e32 v245, 0xffff0000, v245
	v_sub_f32_e32 v243, v243, v250
	v_sub_f32_e32 v242, v242, v250
	v_sub_f32_e32 v197, v197, v250
	v_sub_f32_e32 v196, v196, v250
	v_pk_mul_f32 v[196:197], v[250:251], v[196:197] op_sel:[1,0]
	v_pk_mul_f32 v[242:243], v[250:251], v[242:243] op_sel:[1,0]
	v_sub_f32_e32 v245, v245, v250
	v_sub_f32_e32 v244, v244, v250
	v_sub_f32_e32 v187, v187, v250
	v_sub_f32_e32 v186, v186, v250
	v_pk_fma_f32 v[242:243], v[76:77], v[242:243], v[80:81]
	v_pk_fma_f32 v[196:197], v[74:75], v[196:197], v[78:79]
	v_pk_mul_f32 v[186:187], v[250:251], v[186:187] op_sel:[1,0]
	v_pk_mul_f32 v[244:245], v[250:251], v[244:245] op_sel:[1,0]
	v_pk_fma_f32 v[186:187], v[66:67], v[186:187], v[70:71]
	v_pk_fma_f32 v[244:245], v[68:69], v[244:245], v[72:73]
	v_pk_mul_f32 v[242:243], v[242:243], s[56:57] op_sel_hi:[1,0]
	v_pk_mul_f32 v[196:197], v[196:197], s[56:57] op_sel_hi:[1,0]
	v_pk_mul_f32 v[244:245], v[244:245], s[56:57] op_sel_hi:[1,0]
	v_pk_mul_f32 v[186:187], v[186:187], s[56:57] op_sel_hi:[1,0]
	v_pk_fma_f32 v[160:161], v[160:161], v[64:65], v[242:243]
	v_pk_fma_f32 v[158:159], v[158:159], v[62:63], v[196:197]
	v_pk_fma_f32 v[156:157], v[156:157], v[60:61], v[244:245]
	v_pk_fma_f32 v[154:155], v[154:155], v[58:59], v[186:187]
	v_cvt_pk_bf16_f32 v158, v158, v159
	v_cvt_pk_bf16_f32 v159, v160, v161
	v_cvt_pk_bf16_f32 v160, v154, v155
	v_cvt_pk_bf16_f32 v161, v156, v157
	global_store_dwordx4 v[184:185], v[158:161], off
	s_waitcnt vmcnt(9)
	v_lshlrev_b32_e32 v196, 16, v246
	v_and_b32_e32 v197, 0xffff0000, v246
	v_lshlrev_b32_e32 v246, 16, v247
	v_and_b32_e32 v247, 0xffff0000, v247
	v_lshlrev_b32_e32 v186, 16, v248
	v_and_b32_e32 v187, 0xffff0000, v248
	v_lshlrev_b32_e32 v248, 16, v249
	v_and_b32_e32 v249, 0xffff0000, v249
	v_sub_f32_e32 v247, v247, v250
	v_sub_f32_e32 v246, v246, v250
	v_sub_f32_e32 v197, v197, v250
	v_sub_f32_e32 v196, v196, v250
	v_pk_mul_f32 v[196:197], v[250:251], v[196:197] op_sel:[1,0]
	v_pk_mul_f32 v[246:247], v[250:251], v[246:247] op_sel:[1,0]
	v_sub_f32_e32 v249, v249, v250
	v_sub_f32_e32 v248, v248, v250
	v_sub_f32_e32 v187, v187, v250
	v_sub_f32_e32 v186, v186, v250
	v_pk_fma_f32 v[246:247], v[36:37], v[246:247], v[40:41]
	v_pk_fma_f32 v[196:197], v[34:35], v[196:197], v[38:39]
	v_pk_mul_f32 v[186:187], v[250:251], v[186:187] op_sel:[1,0]
	v_pk_mul_f32 v[248:249], v[250:251], v[248:249] op_sel:[1,0]
	v_pk_fma_f32 v[186:187], v[26:27], v[186:187], v[30:31]
	v_pk_fma_f32 v[248:249], v[28:29], v[248:249], v[32:33]
	v_pk_mul_f32 v[246:247], v[246:247], s[56:57] op_sel_hi:[1,0]
	v_pk_mul_f32 v[196:197], v[196:197], s[56:57] op_sel_hi:[1,0]
	v_pk_mul_f32 v[248:249], v[248:249], s[56:57] op_sel_hi:[1,0]
	v_pk_mul_f32 v[186:187], v[186:187], s[56:57] op_sel_hi:[1,0]
	v_pk_fma_f32 v[152:153], v[152:153], v[24:25], v[246:247]
	v_pk_fma_f32 v[150:151], v[150:151], v[22:23], v[196:197]
	v_pk_fma_f32 v[148:149], v[148:149], v[20:21], v[248:249]
	v_pk_fma_f32 v[146:147], v[146:147], v[18:19], v[186:187]
	v_cvt_pk_bf16_f32 v150, v150, v151
	v_cvt_pk_bf16_f32 v151, v152, v153
	v_cvt_pk_bf16_f32 v152, v146, v147
	v_cvt_pk_bf16_f32 v153, v148, v149
	global_store_dwordx4 v[184:185], v[150:153], off offset:256
	s_mov_b32 s0, 0x8000
	v_lshl_add_u64 v[184:185], v[184:185], 0, s[0:1]
	global_load_dwordx2 v[250:251], v[194:195], off offset:1024
	global_load_dwordx4 v[242:245], v[188:189], off
	global_load_dwordx4 v[246:249], v[188:189], off offset:256
	v_lshl_add_u64 v[188:189], v[188:189], 0, s[0:1]
	s_waitcnt vmcnt(11)
	v_lshlrev_b32_e32 v196, 16, v218
	v_and_b32_e32 v197, 0xffff0000, v218
	v_lshlrev_b32_e32 v218, 16, v219
	v_and_b32_e32 v219, 0xffff0000, v219
	v_lshlrev_b32_e32 v186, 16, v220
	v_and_b32_e32 v187, 0xffff0000, v220
	v_lshlrev_b32_e32 v220, 16, v221
	v_and_b32_e32 v221, 0xffff0000, v221
	v_sub_f32_e32 v219, v219, v222
	v_sub_f32_e32 v218, v218, v222
	v_sub_f32_e32 v197, v197, v222
	v_sub_f32_e32 v196, v196, v222
	v_pk_mul_f32 v[196:197], v[222:223], v[196:197] op_sel:[1,0]
	v_pk_mul_f32 v[218:219], v[222:223], v[218:219] op_sel:[1,0]
	v_sub_f32_e32 v221, v221, v222
	v_sub_f32_e32 v220, v220, v222
	v_sub_f32_e32 v187, v187, v222
	v_sub_f32_e32 v186, v186, v222
	v_pk_fma_f32 v[218:219], v[76:77], v[218:219], v[80:81]
	v_pk_fma_f32 v[196:197], v[74:75], v[196:197], v[78:79]
	v_pk_mul_f32 v[186:187], v[222:223], v[186:187] op_sel:[1,0]
	v_pk_mul_f32 v[220:221], v[222:223], v[220:221] op_sel:[1,0]
	v_pk_fma_f32 v[186:187], v[66:67], v[186:187], v[70:71]
	v_pk_fma_f32 v[220:221], v[68:69], v[220:221], v[72:73]
	v_pk_mul_f32 v[218:219], v[218:219], s[56:57] op_sel_hi:[1,0]
	v_pk_mul_f32 v[196:197], v[196:197], s[56:57] op_sel_hi:[1,0]
	v_pk_mul_f32 v[220:221], v[220:221], s[56:57] op_sel_hi:[1,0]
	v_pk_mul_f32 v[186:187], v[186:187], s[56:57] op_sel_hi:[1,0]
	v_pk_fma_f32 v[144:145], v[144:145], v[64:65], v[218:219]
	v_pk_fma_f32 v[142:143], v[142:143], v[62:63], v[196:197]
	v_pk_fma_f32 v[140:141], v[140:141], v[60:61], v[220:221]
	v_pk_fma_f32 v[138:139], v[138:139], v[58:59], v[186:187]
	v_cvt_pk_bf16_f32 v142, v142, v143
	v_cvt_pk_bf16_f32 v143, v144, v145
	v_cvt_pk_bf16_f32 v144, v138, v139
	v_cvt_pk_bf16_f32 v145, v140, v141
	global_store_dwordx4 v[184:185], v[142:145], off
	s_waitcnt vmcnt(11)
	v_lshlrev_b32_e32 v196, 16, v206
	v_and_b32_e32 v197, 0xffff0000, v206
	v_lshlrev_b32_e32 v206, 16, v207
	v_and_b32_e32 v207, 0xffff0000, v207
	v_lshlrev_b32_e32 v186, 16, v208
	v_and_b32_e32 v187, 0xffff0000, v208
	v_lshlrev_b32_e32 v208, 16, v209
	v_and_b32_e32 v209, 0xffff0000, v209
	v_sub_f32_e32 v207, v207, v222
	v_sub_f32_e32 v206, v206, v222
	v_sub_f32_e32 v197, v197, v222
	v_sub_f32_e32 v196, v196, v222
	v_pk_mul_f32 v[196:197], v[222:223], v[196:197] op_sel:[1,0]
	v_pk_mul_f32 v[206:207], v[222:223], v[206:207] op_sel:[1,0]
	v_sub_f32_e32 v209, v209, v222
	v_sub_f32_e32 v208, v208, v222
	v_sub_f32_e32 v187, v187, v222
	v_sub_f32_e32 v186, v186, v222
	v_pk_fma_f32 v[206:207], v[36:37], v[206:207], v[40:41]
	v_pk_fma_f32 v[196:197], v[34:35], v[196:197], v[38:39]
	v_pk_mul_f32 v[186:187], v[222:223], v[186:187] op_sel:[1,0]
	v_pk_mul_f32 v[208:209], v[222:223], v[208:209] op_sel:[1,0]
	v_pk_fma_f32 v[186:187], v[26:27], v[186:187], v[30:31]
	v_pk_fma_f32 v[208:209], v[28:29], v[208:209], v[32:33]
	v_pk_mul_f32 v[206:207], v[206:207], s[56:57] op_sel_hi:[1,0]
	v_pk_mul_f32 v[196:197], v[196:197], s[56:57] op_sel_hi:[1,0]
	v_pk_mul_f32 v[208:209], v[208:209], s[56:57] op_sel_hi:[1,0]
	v_pk_mul_f32 v[186:187], v[186:187], s[56:57] op_sel_hi:[1,0]
	v_pk_fma_f32 v[136:137], v[136:137], v[24:25], v[206:207]
	v_pk_fma_f32 v[134:135], v[134:135], v[22:23], v[196:197]
	v_pk_fma_f32 v[132:133], v[132:133], v[20:21], v[208:209]
	v_pk_fma_f32 v[130:131], v[130:131], v[18:19], v[186:187]
	v_cvt_pk_bf16_f32 v134, v134, v135
	v_cvt_pk_bf16_f32 v135, v136, v137
	v_cvt_pk_bf16_f32 v136, v130, v131
	v_cvt_pk_bf16_f32 v137, v132, v133
	global_store_dwordx4 v[184:185], v[134:137], off offset:256
	v_lshl_add_u64 v[184:185], v[184:185], 0, s[0:1]
	global_load_dwordx2 v[222:223], v[194:195], off offset:1152
	global_load_dwordx4 v[218:221], v[188:189], off
	global_load_dwordx4 v[206:209], v[188:189], off offset:256
	v_lshl_add_u64 v[188:189], v[188:189], 0, s[0:1]
	s_waitcnt vmcnt(11)
	v_lshlrev_b32_e32 v196, 16, v210
	v_and_b32_e32 v197, 0xffff0000, v210
	v_lshlrev_b32_e32 v210, 16, v211
	v_and_b32_e32 v211, 0xffff0000, v211
	v_lshlrev_b32_e32 v186, 16, v212
	v_and_b32_e32 v187, 0xffff0000, v212
	v_lshlrev_b32_e32 v212, 16, v213
	v_and_b32_e32 v213, 0xffff0000, v213
	v_sub_f32_e32 v211, v211, v232
	v_sub_f32_e32 v210, v210, v232
	v_sub_f32_e32 v197, v197, v232
	v_sub_f32_e32 v196, v196, v232
	v_pk_mul_f32 v[196:197], v[232:233], v[196:197] op_sel:[1,0]
	v_pk_mul_f32 v[210:211], v[232:233], v[210:211] op_sel:[1,0]
	v_sub_f32_e32 v213, v213, v232
	v_sub_f32_e32 v212, v212, v232
	v_sub_f32_e32 v187, v187, v232
	v_sub_f32_e32 v186, v186, v232
	v_pk_fma_f32 v[210:211], v[76:77], v[210:211], v[80:81]
	v_pk_fma_f32 v[196:197], v[74:75], v[196:197], v[78:79]
	v_pk_mul_f32 v[186:187], v[232:233], v[186:187] op_sel:[1,0]
	v_pk_mul_f32 v[212:213], v[232:233], v[212:213] op_sel:[1,0]
	v_pk_fma_f32 v[186:187], v[66:67], v[186:187], v[70:71]
	v_pk_fma_f32 v[212:213], v[68:69], v[212:213], v[72:73]
	v_pk_mul_f32 v[210:211], v[210:211], s[56:57] op_sel_hi:[1,0]
	v_pk_mul_f32 v[196:197], v[196:197], s[56:57] op_sel_hi:[1,0]
	v_pk_mul_f32 v[212:213], v[212:213], s[56:57] op_sel_hi:[1,0]
	v_pk_mul_f32 v[186:187], v[186:187], s[56:57] op_sel_hi:[1,0]
	v_pk_fma_f32 v[128:129], v[128:129], v[64:65], v[210:211]
	v_pk_fma_f32 v[126:127], v[126:127], v[62:63], v[196:197]
	v_pk_fma_f32 v[124:125], v[124:125], v[60:61], v[212:213]
	v_pk_fma_f32 v[122:123], v[122:123], v[58:59], v[186:187]
	v_cvt_pk_bf16_f32 v126, v126, v127
	v_cvt_pk_bf16_f32 v127, v128, v129
	v_cvt_pk_bf16_f32 v128, v122, v123
	v_cvt_pk_bf16_f32 v129, v124, v125
	global_store_dwordx4 v[184:185], v[126:129], off
	s_waitcnt vmcnt(11)
	v_lshlrev_b32_e32 v196, 16, v214
	v_and_b32_e32 v197, 0xffff0000, v214
	v_lshlrev_b32_e32 v214, 16, v215
	v_and_b32_e32 v215, 0xffff0000, v215
	v_lshlrev_b32_e32 v186, 16, v216
	v_and_b32_e32 v187, 0xffff0000, v216
	v_lshlrev_b32_e32 v216, 16, v217
	v_and_b32_e32 v217, 0xffff0000, v217
	v_sub_f32_e32 v215, v215, v232
	v_sub_f32_e32 v214, v214, v232
	v_sub_f32_e32 v197, v197, v232
	v_sub_f32_e32 v196, v196, v232
	v_pk_mul_f32 v[196:197], v[232:233], v[196:197] op_sel:[1,0]
	v_pk_mul_f32 v[214:215], v[232:233], v[214:215] op_sel:[1,0]
	v_sub_f32_e32 v217, v217, v232
	v_sub_f32_e32 v216, v216, v232
	v_sub_f32_e32 v187, v187, v232
	v_sub_f32_e32 v186, v186, v232
	v_pk_fma_f32 v[214:215], v[36:37], v[214:215], v[40:41]
	v_pk_fma_f32 v[196:197], v[34:35], v[196:197], v[38:39]
	v_pk_mul_f32 v[186:187], v[232:233], v[186:187] op_sel:[1,0]
	v_pk_mul_f32 v[216:217], v[232:233], v[216:217] op_sel:[1,0]
	v_pk_fma_f32 v[186:187], v[26:27], v[186:187], v[30:31]
	v_pk_fma_f32 v[216:217], v[28:29], v[216:217], v[32:33]
	v_pk_mul_f32 v[214:215], v[214:215], s[56:57] op_sel_hi:[1,0]
	v_pk_mul_f32 v[196:197], v[196:197], s[56:57] op_sel_hi:[1,0]
	v_pk_mul_f32 v[216:217], v[216:217], s[56:57] op_sel_hi:[1,0]
	v_pk_mul_f32 v[186:187], v[186:187], s[56:57] op_sel_hi:[1,0]
	v_pk_fma_f32 v[120:121], v[120:121], v[24:25], v[214:215]
	v_pk_fma_f32 v[118:119], v[118:119], v[22:23], v[196:197]
	v_pk_fma_f32 v[116:117], v[116:117], v[20:21], v[216:217]
	v_pk_fma_f32 v[114:115], v[114:115], v[18:19], v[186:187]
	v_cvt_pk_bf16_f32 v118, v118, v119
	v_cvt_pk_bf16_f32 v119, v120, v121
	v_cvt_pk_bf16_f32 v120, v114, v115
	v_cvt_pk_bf16_f32 v121, v116, v117
	global_store_dwordx4 v[184:185], v[118:121], off offset:256
	s_mov_b32 s0, 0x28000
	v_lshl_add_u64 v[184:185], v[184:185], 0, s[0:1]
	global_load_dwordx2 v[232:233], v[194:195], off offset:1280
	global_load_dwordx4 v[210:213], v[188:189], off
	global_load_dwordx4 v[214:217], v[188:189], off offset:256
	s_mov_b32 s0, 0x8000
	v_lshl_add_u64 v[188:189], v[188:189], 0, s[0:1]
	s_waitcnt vmcnt(11)
	v_lshlrev_b32_e32 v196, 16, v242
	v_and_b32_e32 v197, 0xffff0000, v242
	v_lshlrev_b32_e32 v242, 16, v243
	v_and_b32_e32 v243, 0xffff0000, v243
	v_lshlrev_b32_e32 v186, 16, v244
	v_and_b32_e32 v187, 0xffff0000, v244
	v_lshlrev_b32_e32 v244, 16, v245
	v_and_b32_e32 v245, 0xffff0000, v245
	v_sub_f32_e32 v243, v243, v250
	v_sub_f32_e32 v242, v242, v250
	v_sub_f32_e32 v197, v197, v250
	v_sub_f32_e32 v196, v196, v250
	v_pk_mul_f32 v[196:197], v[250:251], v[196:197] op_sel:[1,0]
	v_pk_mul_f32 v[242:243], v[250:251], v[242:243] op_sel:[1,0]
	v_sub_f32_e32 v245, v245, v250
	v_sub_f32_e32 v244, v244, v250
	v_sub_f32_e32 v187, v187, v250
	v_sub_f32_e32 v186, v186, v250
	v_pk_fma_f32 v[242:243], v[76:77], v[242:243], v[80:81]
	v_pk_fma_f32 v[196:197], v[74:75], v[196:197], v[78:79]
	v_pk_mul_f32 v[186:187], v[250:251], v[186:187] op_sel:[1,0]
	v_pk_mul_f32 v[244:245], v[250:251], v[244:245] op_sel:[1,0]
	v_pk_fma_f32 v[186:187], v[66:67], v[186:187], v[70:71]
	v_pk_fma_f32 v[244:245], v[68:69], v[244:245], v[72:73]
	v_pk_mul_f32 v[242:243], v[242:243], s[56:57] op_sel_hi:[1,0]
	v_pk_mul_f32 v[196:197], v[196:197], s[56:57] op_sel_hi:[1,0]
	v_pk_mul_f32 v[244:245], v[244:245], s[56:57] op_sel_hi:[1,0]
	v_pk_mul_f32 v[186:187], v[186:187], s[56:57] op_sel_hi:[1,0]
	v_pk_fma_f32 v[112:113], v[112:113], v[64:65], v[242:243]
	v_pk_fma_f32 v[110:111], v[110:111], v[62:63], v[196:197]
	v_pk_fma_f32 v[108:109], v[108:109], v[60:61], v[244:245]
	v_pk_fma_f32 v[106:107], v[106:107], v[58:59], v[186:187]
	v_cvt_pk_bf16_f32 v110, v110, v111
	v_cvt_pk_bf16_f32 v111, v112, v113
	v_cvt_pk_bf16_f32 v112, v106, v107
	v_cvt_pk_bf16_f32 v113, v108, v109
	global_store_dwordx4 v[184:185], v[110:113], off
	s_waitcnt vmcnt(11)
	v_lshlrev_b32_e32 v196, 16, v246
	v_and_b32_e32 v197, 0xffff0000, v246
	v_lshlrev_b32_e32 v246, 16, v247
	v_and_b32_e32 v247, 0xffff0000, v247
	v_lshlrev_b32_e32 v186, 16, v248
	v_and_b32_e32 v187, 0xffff0000, v248
	v_lshlrev_b32_e32 v248, 16, v249
	v_and_b32_e32 v249, 0xffff0000, v249
	v_sub_f32_e32 v247, v247, v250
	v_sub_f32_e32 v246, v246, v250
	v_sub_f32_e32 v197, v197, v250
	v_sub_f32_e32 v196, v196, v250
	v_pk_mul_f32 v[196:197], v[250:251], v[196:197] op_sel:[1,0]
	v_pk_mul_f32 v[246:247], v[250:251], v[246:247] op_sel:[1,0]
	v_sub_f32_e32 v249, v249, v250
	v_sub_f32_e32 v248, v248, v250
	v_sub_f32_e32 v187, v187, v250
	v_sub_f32_e32 v186, v186, v250
	v_pk_fma_f32 v[246:247], v[36:37], v[246:247], v[40:41]
	v_pk_fma_f32 v[196:197], v[34:35], v[196:197], v[38:39]
	v_pk_mul_f32 v[186:187], v[250:251], v[186:187] op_sel:[1,0]
	v_pk_mul_f32 v[248:249], v[250:251], v[248:249] op_sel:[1,0]
	v_pk_fma_f32 v[186:187], v[26:27], v[186:187], v[30:31]
	v_pk_fma_f32 v[248:249], v[28:29], v[248:249], v[32:33]
	v_pk_mul_f32 v[246:247], v[246:247], s[56:57] op_sel_hi:[1,0]
	v_pk_mul_f32 v[196:197], v[196:197], s[56:57] op_sel_hi:[1,0]
	v_pk_mul_f32 v[248:249], v[248:249], s[56:57] op_sel_hi:[1,0]
	v_pk_mul_f32 v[186:187], v[186:187], s[56:57] op_sel_hi:[1,0]
	v_pk_fma_f32 v[104:105], v[104:105], v[24:25], v[246:247]
	v_pk_fma_f32 v[102:103], v[102:103], v[22:23], v[196:197]
	v_pk_fma_f32 v[100:101], v[100:101], v[20:21], v[248:249]
	v_pk_fma_f32 v[98:99], v[98:99], v[18:19], v[186:187]
	v_cvt_pk_bf16_f32 v102, v102, v103
	v_cvt_pk_bf16_f32 v103, v104, v105
	v_cvt_pk_bf16_f32 v104, v98, v99
	v_cvt_pk_bf16_f32 v105, v100, v101
	global_store_dwordx4 v[184:185], v[102:105], off offset:256
	v_lshl_add_u64 v[184:185], v[184:185], 0, s[0:1]
	global_load_dwordx2 v[250:251], v[194:195], off offset:1408
	global_load_dwordx4 v[242:245], v[188:189], off
	global_load_dwordx4 v[246:249], v[188:189], off offset:256
	s_waitcnt vmcnt(11)
	v_lshlrev_b32_e32 v196, 16, v218
	v_and_b32_e32 v197, 0xffff0000, v218
	v_lshlrev_b32_e32 v218, 16, v219
	v_and_b32_e32 v219, 0xffff0000, v219
	v_lshlrev_b32_e32 v186, 16, v220
	v_and_b32_e32 v187, 0xffff0000, v220
	v_lshlrev_b32_e32 v220, 16, v221
	v_and_b32_e32 v221, 0xffff0000, v221
	v_sub_f32_e32 v219, v219, v222
	v_sub_f32_e32 v218, v218, v222
	v_sub_f32_e32 v197, v197, v222
	v_sub_f32_e32 v196, v196, v222
	v_pk_mul_f32 v[196:197], v[222:223], v[196:197] op_sel:[1,0]
	v_pk_mul_f32 v[218:219], v[222:223], v[218:219] op_sel:[1,0]
	v_sub_f32_e32 v221, v221, v222
	v_sub_f32_e32 v220, v220, v222
	v_sub_f32_e32 v187, v187, v222
	v_sub_f32_e32 v186, v186, v222
	v_pk_fma_f32 v[218:219], v[76:77], v[218:219], v[80:81]
	v_pk_fma_f32 v[196:197], v[74:75], v[196:197], v[78:79]
	v_pk_mul_f32 v[186:187], v[222:223], v[186:187] op_sel:[1,0]
	v_pk_mul_f32 v[220:221], v[222:223], v[220:221] op_sel:[1,0]
	v_pk_fma_f32 v[186:187], v[66:67], v[186:187], v[70:71]
	v_pk_fma_f32 v[220:221], v[68:69], v[220:221], v[72:73]
	v_pk_mul_f32 v[218:219], v[218:219], s[56:57] op_sel_hi:[1,0]
	v_pk_mul_f32 v[196:197], v[196:197], s[56:57] op_sel_hi:[1,0]
	v_pk_mul_f32 v[220:221], v[220:221], s[56:57] op_sel_hi:[1,0]
	v_pk_mul_f32 v[186:187], v[186:187], s[56:57] op_sel_hi:[1,0]
	v_pk_fma_f32 v[96:97], v[96:97], v[64:65], v[218:219]
	v_pk_fma_f32 v[94:95], v[94:95], v[62:63], v[196:197]
	v_pk_fma_f32 v[92:93], v[92:93], v[60:61], v[220:221]
	v_pk_fma_f32 v[90:91], v[90:91], v[58:59], v[186:187]
	v_cvt_pk_bf16_f32 v94, v94, v95
	v_cvt_pk_bf16_f32 v95, v96, v97
	v_cvt_pk_bf16_f32 v96, v90, v91
	v_cvt_pk_bf16_f32 v97, v92, v93
	global_store_dwordx4 v[184:185], v[94:97], off
	s_waitcnt vmcnt(11)
	v_lshlrev_b32_e32 v196, 16, v206
	v_and_b32_e32 v197, 0xffff0000, v206
	v_lshlrev_b32_e32 v206, 16, v207
	v_and_b32_e32 v207, 0xffff0000, v207
	v_lshlrev_b32_e32 v186, 16, v208
	v_and_b32_e32 v187, 0xffff0000, v208
	v_lshlrev_b32_e32 v208, 16, v209
	v_and_b32_e32 v209, 0xffff0000, v209
	v_sub_f32_e32 v207, v207, v222
	v_sub_f32_e32 v206, v206, v222
	v_sub_f32_e32 v197, v197, v222
	v_sub_f32_e32 v196, v196, v222
	v_pk_mul_f32 v[196:197], v[222:223], v[196:197] op_sel:[1,0]
	v_pk_mul_f32 v[206:207], v[222:223], v[206:207] op_sel:[1,0]
	v_sub_f32_e32 v209, v209, v222
	v_sub_f32_e32 v208, v208, v222
	v_sub_f32_e32 v187, v187, v222
	v_sub_f32_e32 v186, v186, v222
	v_pk_fma_f32 v[206:207], v[36:37], v[206:207], v[40:41]
	v_pk_fma_f32 v[196:197], v[34:35], v[196:197], v[38:39]
	v_pk_mul_f32 v[186:187], v[222:223], v[186:187] op_sel:[1,0]
	v_pk_mul_f32 v[208:209], v[222:223], v[208:209] op_sel:[1,0]
	v_pk_fma_f32 v[186:187], v[26:27], v[186:187], v[30:31]
	v_pk_fma_f32 v[208:209], v[28:29], v[208:209], v[32:33]
	v_pk_mul_f32 v[206:207], v[206:207], s[56:57] op_sel_hi:[1,0]
	v_pk_mul_f32 v[196:197], v[196:197], s[56:57] op_sel_hi:[1,0]
	v_pk_mul_f32 v[208:209], v[208:209], s[56:57] op_sel_hi:[1,0]
	v_pk_mul_f32 v[186:187], v[186:187], s[56:57] op_sel_hi:[1,0]
	v_pk_fma_f32 v[88:89], v[88:89], v[24:25], v[206:207]
	v_pk_fma_f32 v[86:87], v[86:87], v[22:23], v[196:197]
	v_pk_fma_f32 v[84:85], v[84:85], v[20:21], v[208:209]
	v_pk_fma_f32 v[82:83], v[82:83], v[18:19], v[186:187]
	v_cvt_pk_bf16_f32 v86, v86, v87
	v_cvt_pk_bf16_f32 v87, v88, v89
	v_cvt_pk_bf16_f32 v88, v82, v83
	v_cvt_pk_bf16_f32 v89, v84, v85
	global_store_dwordx4 v[184:185], v[86:89], off offset:256
	v_lshl_add_u64 v[184:185], v[184:185], 0, s[0:1]
	s_waitcnt vmcnt(8)
	v_lshlrev_b32_e32 v196, 16, v210
	v_and_b32_e32 v197, 0xffff0000, v210
	v_lshlrev_b32_e32 v210, 16, v211
	v_and_b32_e32 v211, 0xffff0000, v211
	v_lshlrev_b32_e32 v186, 16, v212
	v_and_b32_e32 v187, 0xffff0000, v212
	v_lshlrev_b32_e32 v212, 16, v213
	v_and_b32_e32 v213, 0xffff0000, v213
	v_sub_f32_e32 v211, v211, v232
	v_sub_f32_e32 v210, v210, v232
	v_sub_f32_e32 v197, v197, v232
	v_sub_f32_e32 v196, v196, v232
	v_pk_mul_f32 v[196:197], v[232:233], v[196:197] op_sel:[1,0]
	v_pk_mul_f32 v[210:211], v[232:233], v[210:211] op_sel:[1,0]
	v_sub_f32_e32 v213, v213, v232
	v_sub_f32_e32 v212, v212, v232
	v_sub_f32_e32 v187, v187, v232
	v_sub_f32_e32 v186, v186, v232
	v_pk_fma_f32 v[210:211], v[76:77], v[210:211], v[80:81]
	v_pk_fma_f32 v[196:197], v[74:75], v[196:197], v[78:79]
	v_pk_mul_f32 v[186:187], v[232:233], v[186:187] op_sel:[1,0]
	v_pk_mul_f32 v[212:213], v[232:233], v[212:213] op_sel:[1,0]
	v_pk_fma_f32 v[186:187], v[66:67], v[186:187], v[70:71]
	v_pk_fma_f32 v[212:213], v[68:69], v[212:213], v[72:73]
	v_pk_mul_f32 v[210:211], v[210:211], s[56:57] op_sel_hi:[1,0]
	v_pk_mul_f32 v[196:197], v[196:197], s[56:57] op_sel_hi:[1,0]
	v_pk_mul_f32 v[212:213], v[212:213], s[56:57] op_sel_hi:[1,0]
	v_pk_mul_f32 v[186:187], v[186:187], s[56:57] op_sel_hi:[1,0]
	v_pk_fma_f32 v[56:57], v[56:57], v[64:65], v[210:211]
	v_pk_fma_f32 v[54:55], v[54:55], v[62:63], v[196:197]
	v_pk_fma_f32 v[52:53], v[52:53], v[60:61], v[212:213]
	v_pk_fma_f32 v[50:51], v[50:51], v[58:59], v[186:187]
	v_cvt_pk_bf16_f32 v54, v54, v55
	v_cvt_pk_bf16_f32 v55, v56, v57
	v_cvt_pk_bf16_f32 v56, v50, v51
	v_cvt_pk_bf16_f32 v57, v52, v53
	global_store_dwordx4 v[184:185], v[54:57], off
	s_waitcnt vmcnt(8)
	v_lshlrev_b32_e32 v196, 16, v214
	v_and_b32_e32 v197, 0xffff0000, v214
	v_lshlrev_b32_e32 v214, 16, v215
	v_and_b32_e32 v215, 0xffff0000, v215
	v_lshlrev_b32_e32 v186, 16, v216
	v_and_b32_e32 v187, 0xffff0000, v216
	v_lshlrev_b32_e32 v216, 16, v217
	v_and_b32_e32 v217, 0xffff0000, v217
	v_sub_f32_e32 v215, v215, v232
	v_sub_f32_e32 v214, v214, v232
	v_sub_f32_e32 v197, v197, v232
	v_sub_f32_e32 v196, v196, v232
	v_pk_mul_f32 v[196:197], v[232:233], v[196:197] op_sel:[1,0]
	v_pk_mul_f32 v[214:215], v[232:233], v[214:215] op_sel:[1,0]
	v_sub_f32_e32 v217, v217, v232
	v_sub_f32_e32 v216, v216, v232
	v_sub_f32_e32 v187, v187, v232
	v_sub_f32_e32 v186, v186, v232
	v_pk_fma_f32 v[214:215], v[36:37], v[214:215], v[40:41]
	v_pk_fma_f32 v[196:197], v[34:35], v[196:197], v[38:39]
	v_pk_mul_f32 v[186:187], v[232:233], v[186:187] op_sel:[1,0]
	v_pk_mul_f32 v[216:217], v[232:233], v[216:217] op_sel:[1,0]
	v_pk_fma_f32 v[186:187], v[26:27], v[186:187], v[30:31]
	v_pk_fma_f32 v[216:217], v[28:29], v[216:217], v[32:33]
	v_pk_mul_f32 v[214:215], v[214:215], s[56:57] op_sel_hi:[1,0]
	v_pk_mul_f32 v[196:197], v[196:197], s[56:57] op_sel_hi:[1,0]
	v_pk_mul_f32 v[216:217], v[216:217], s[56:57] op_sel_hi:[1,0]
	v_pk_mul_f32 v[186:187], v[186:187], s[56:57] op_sel_hi:[1,0]
	v_pk_fma_f32 v[48:49], v[48:49], v[24:25], v[214:215]
	v_pk_fma_f32 v[46:47], v[46:47], v[22:23], v[196:197]
	v_pk_fma_f32 v[44:45], v[44:45], v[20:21], v[216:217]
	v_pk_fma_f32 v[42:43], v[42:43], v[18:19], v[186:187]
	v_cvt_pk_bf16_f32 v46, v46, v47
	v_cvt_pk_bf16_f32 v47, v48, v49
	v_cvt_pk_bf16_f32 v48, v42, v43
	v_cvt_pk_bf16_f32 v49, v44, v45
	global_store_dwordx4 v[184:185], v[46:49], off offset:256
	v_lshl_add_u64 v[184:185], v[184:185], 0, s[0:1]
	s_waitcnt vmcnt(5)
	v_lshlrev_b32_e32 v196, 16, v242
	v_and_b32_e32 v197, 0xffff0000, v242
	v_lshlrev_b32_e32 v242, 16, v243
	v_and_b32_e32 v243, 0xffff0000, v243
	v_lshlrev_b32_e32 v186, 16, v244
	v_and_b32_e32 v187, 0xffff0000, v244
	v_lshlrev_b32_e32 v244, 16, v245
	v_and_b32_e32 v245, 0xffff0000, v245
	v_sub_f32_e32 v243, v243, v250
	v_sub_f32_e32 v242, v242, v250
	v_sub_f32_e32 v197, v197, v250
	v_sub_f32_e32 v196, v196, v250
	v_pk_mul_f32 v[196:197], v[250:251], v[196:197] op_sel:[1,0]
	v_pk_mul_f32 v[242:243], v[250:251], v[242:243] op_sel:[1,0]
	v_sub_f32_e32 v245, v245, v250
	v_sub_f32_e32 v244, v244, v250
	v_sub_f32_e32 v187, v187, v250
	v_sub_f32_e32 v186, v186, v250
	v_pk_fma_f32 v[242:243], v[76:77], v[242:243], v[80:81]
	v_pk_fma_f32 v[196:197], v[74:75], v[196:197], v[78:79]
	v_pk_mul_f32 v[186:187], v[250:251], v[186:187] op_sel:[1,0]
	v_pk_mul_f32 v[244:245], v[250:251], v[244:245] op_sel:[1,0]
	v_pk_fma_f32 v[186:187], v[66:67], v[186:187], v[70:71]
	v_pk_fma_f32 v[244:245], v[68:69], v[244:245], v[72:73]
	v_pk_mul_f32 v[242:243], v[242:243], s[56:57] op_sel_hi:[1,0]
	v_pk_mul_f32 v[196:197], v[196:197], s[56:57] op_sel_hi:[1,0]
	v_pk_mul_f32 v[244:245], v[244:245], s[56:57] op_sel_hi:[1,0]
	v_pk_mul_f32 v[186:187], v[186:187], s[56:57] op_sel_hi:[1,0]
	v_pk_fma_f32 v[16:17], v[16:17], v[64:65], v[242:243]
	v_pk_fma_f32 v[14:15], v[14:15], v[62:63], v[196:197]
	v_pk_fma_f32 v[12:13], v[12:13], v[60:61], v[244:245]
	v_pk_fma_f32 v[10:11], v[10:11], v[58:59], v[186:187]
	v_cvt_pk_bf16_f32 v14, v14, v15
	v_cvt_pk_bf16_f32 v15, v16, v17
	v_cvt_pk_bf16_f32 v16, v10, v11
	v_cvt_pk_bf16_f32 v17, v12, v13
	global_store_dwordx4 v[184:185], v[14:17], off
	s_waitcnt vmcnt(5)
	v_lshlrev_b32_e32 v196, 16, v246
	v_and_b32_e32 v197, 0xffff0000, v246
	v_lshlrev_b32_e32 v246, 16, v247
	v_and_b32_e32 v247, 0xffff0000, v247
	v_lshlrev_b32_e32 v186, 16, v248
	v_and_b32_e32 v187, 0xffff0000, v248
	v_lshlrev_b32_e32 v248, 16, v249
	v_and_b32_e32 v249, 0xffff0000, v249
	v_sub_f32_e32 v247, v247, v250
	v_sub_f32_e32 v246, v246, v250
	v_sub_f32_e32 v197, v197, v250
	v_sub_f32_e32 v196, v196, v250
	v_pk_mul_f32 v[196:197], v[250:251], v[196:197] op_sel:[1,0]
	v_pk_mul_f32 v[246:247], v[250:251], v[246:247] op_sel:[1,0]
	v_sub_f32_e32 v249, v249, v250
	v_sub_f32_e32 v248, v248, v250
	v_sub_f32_e32 v187, v187, v250
	v_sub_f32_e32 v186, v186, v250
	v_pk_fma_f32 v[246:247], v[36:37], v[246:247], v[40:41]
	v_pk_fma_f32 v[196:197], v[34:35], v[196:197], v[38:39]
	v_pk_mul_f32 v[186:187], v[250:251], v[186:187] op_sel:[1,0]
	v_pk_mul_f32 v[248:249], v[250:251], v[248:249] op_sel:[1,0]
	v_pk_fma_f32 v[186:187], v[26:27], v[186:187], v[30:31]
	v_pk_fma_f32 v[248:249], v[28:29], v[248:249], v[32:33]
	v_pk_mul_f32 v[246:247], v[246:247], s[56:57] op_sel_hi:[1,0]
	v_pk_mul_f32 v[196:197], v[196:197], s[56:57] op_sel_hi:[1,0]
	v_pk_mul_f32 v[248:249], v[248:249], s[56:57] op_sel_hi:[1,0]
	v_pk_mul_f32 v[186:187], v[186:187], s[56:57] op_sel_hi:[1,0]
	v_pk_fma_f32 v[8:9], v[8:9], v[24:25], v[246:247]
	v_pk_fma_f32 v[6:7], v[6:7], v[22:23], v[196:197]
	v_pk_fma_f32 v[4:5], v[4:5], v[20:21], v[248:249]
	v_pk_fma_f32 v[2:3], v[2:3], v[18:19], v[186:187]
	v_cvt_pk_bf16_f32 v6, v6, v7
	v_cvt_pk_bf16_f32 v7, v8, v9
	v_cvt_pk_bf16_f32 v8, v2, v3
	v_cvt_pk_bf16_f32 v9, v4, v5
	global_store_dwordx4 v[184:185], v[6:9], off offset:256
	s_cbranch_vccz .LBB0_777
	s_waitcnt vmcnt(0)
	s_cmpk_gt_u32 s19, 0xff
	s_mov_b32 s74, 0x3e75aa41
	s_mov_b32 s72, 0x40490fdb
	s_mov_b32 s80, 0xc0a55e0e
	s_brev_b32 s64, 60
	s_cbranch_scc1 .LBB0_784
	s_barrier
